# three P1 conversion classes, fractions 1/8 first, 4/8 between the GEMM1 calls, 3/8 after
# baseline (speedup 1.0000x reference)
_Z3fwd4Args:
	v_writelane_b32 v249, s0, 0
	v_writelane_b32 v249, s1, 1
	v_writelane_b32 v249, s2, 2
	v_mov_b32_e32 v250, v0
	s_and_b32 s98, s2, 7
	s_movk_i32 s101, 0x100
	s_cmp_lt_u32 s98, 5
	s_cselect_b32 s101, 0x400, s101
	s_cmp_lt_u32 s98, 1
	s_cselect_b32 s101, 0, s101
